# attention QK phase: K fragment LDS reads of k-steps 1-2 hoisted into free register buffers (3 ahead), lgkmcnt waits recomputed
# speedup vs baseline: 1.0271x; 1.0024x over previous
; #define LAS __attribute__((address_space(3)))
; __device__ __forceinline__ void attn_unit(const bf16* proj, unsigned char* ws, LAS unsigned char* lds, int a) {
;     ...
; #pragma unroll
;         for (int s = 0; s < 4; ++s) {
;             const bf16x8 qa = *(const LAS bf16x8*)(qbase + 64 * s), qb = *(const LAS bf16x8*)(qbase + 16 * QK_STRIDE + 64 * s);
; #pragma unroll
;             for (int kt = 0; kt < 8; ++kt) {
;                 const bf16x8 kf = *(const LAS bf16x8*)(KS + (16 * kt + fr) * QK_STRIDE + (32 * s + 8 * fq) * 2);
;                 st[0][kt] = __builtin_amdgcn_mfma_f32_16x16x32_bf16(kf, qa, st[0][kt], 0, 0, 0);
;                 st[1][kt] = __builtin_amdgcn_mfma_f32_16x16x32_bf16(kf, qb, st[1][kt], 0, 0, 0);
;             }
;         }
.LBB0_608:
	ds_read_b128 v[92:95], v205
	ds_read_b128 v[100:103], v205 offset:4352
	ds_read_b128 v[104:107], v201
	ds_read_b128 v[112:115], v201 offset:4352
	ds_read_b128 v[120:123], v201 offset:8704
	ds_read_b128 v[128:131], v201 offset:13056
	ds_read_b128 v[136:139], v201 offset:17408
	ds_read_b128 v[144:147], v201 offset:21760
	ds_read_b128 v[152:155], v201 offset:26112
	ds_read_b128 v[210:213], v201 offset:30464
	s_waitcnt lgkmcnt(7)
	v_mfma_f32_16x16x32_bf16 v[108:111], v[104:107], v[92:95], 0
	s_cmp_lg_u32 s72, s51
	s_cselect_b64 s[56:57], -1, 0
	s_cmp_lt_u32 s70, s69
	v_mfma_f32_16x16x32_bf16 v[104:107], v[104:107], v[100:103], 0
	s_cselect_b64 s[4:5], -1, 0
	v_sub_u32_e32 v207, 0, v181
	v_cndmask_b32_e64 v207, v207, v181, s[4:5]
	s_waitcnt lgkmcnt(6)
	v_mfma_f32_16x16x32_bf16 v[116:119], v[112:115], v[92:95], 0
	s_cmp_eq_u32 s72, s51
	v_mfma_f32_16x16x32_bf16 v[112:115], v[112:115], v[100:103], 0
	s_waitcnt lgkmcnt(5)
	v_mfma_f32_16x16x32_bf16 v[124:127], v[120:123], v[92:95], 0
	v_mfma_f32_16x16x32_bf16 v[120:123], v[120:123], v[100:103], 0
	s_waitcnt lgkmcnt(4)
	v_mfma_f32_16x16x32_bf16 v[132:135], v[128:131], v[92:95], 0
	v_mfma_f32_16x16x32_bf16 v[128:131], v[128:131], v[100:103], 0
	s_waitcnt lgkmcnt(3)
	v_mfma_f32_16x16x32_bf16 v[140:143], v[136:139], v[92:95], 0
	v_mfma_f32_16x16x32_bf16 v[136:139], v[136:139], v[100:103], 0
	ds_read_b128 v[246:249], v201 offset:64
	s_waitcnt lgkmcnt(3)
	v_mfma_f32_16x16x32_bf16 v[148:151], v[144:147], v[92:95], 0
	v_mfma_f32_16x16x32_bf16 v[144:147], v[144:147], v[100:103], 0
	ds_read_b128 v[250:253], v201 offset:4416
	s_waitcnt lgkmcnt(3)
	v_mfma_f32_16x16x32_bf16 v[156:159], v[152:155], v[92:95], 0
	v_mfma_f32_16x16x32_bf16 v[152:155], v[152:155], v[100:103], 0
	ds_read_b128 v[218:221], v201 offset:8768
	s_waitcnt lgkmcnt(3)
	v_mfma_f32_16x16x32_bf16 v[92:95], v[210:213], v[92:95], 0
	v_mfma_f32_16x16x32_bf16 v[100:103], v[210:213], v[100:103], 0
	ds_read_b128 v[210:213], v205 offset:64
	ds_read_b128 v[214:217], v205 offset:4416
	ds_read_b128 v[238:241], v201 offset:13120
	s_waitcnt lgkmcnt(2)
	v_mfma_f32_16x16x32_bf16 v[108:111], v[246:249], v[210:213], v[108:111]
	s_waitcnt lgkmcnt(1)
	v_mfma_f32_16x16x32_bf16 v[104:107], v[246:249], v[214:217], v[104:107]
	ds_read_b128 v[246:249], v201 offset:17472
	v_mfma_f32_16x16x32_bf16 v[116:119], v[250:253], v[210:213], v[116:119]
	v_mfma_f32_16x16x32_bf16 v[112:115], v[250:253], v[214:217], v[112:115]
	ds_read_b128 v[250:253], v201 offset:21824
	v_mfma_f32_16x16x32_bf16 v[124:127], v[218:221], v[210:213], v[124:127]
	v_mfma_f32_16x16x32_bf16 v[120:123], v[218:221], v[214:217], v[120:123]
	ds_read_b128 v[218:221], v201 offset:26176
	s_waitcnt lgkmcnt(3)
	v_mfma_f32_16x16x32_bf16 v[132:135], v[238:241], v[210:213], v[132:135]
	v_mfma_f32_16x16x32_bf16 v[128:131], v[238:241], v[214:217], v[128:131]
	ds_read_b128 v[238:241], v201 offset:30528
	s_waitcnt lgkmcnt(3)
	v_mfma_f32_16x16x32_bf16 v[140:143], v[246:249], v[210:213], v[140:143]
	v_mfma_f32_16x16x32_bf16 v[136:139], v[246:249], v[214:217], v[136:139]
	ds_read_b128 v[246:249], v201 offset:128
	s_waitcnt lgkmcnt(3)
	v_mfma_f32_16x16x32_bf16 v[148:151], v[250:253], v[210:213], v[148:151]
	v_mfma_f32_16x16x32_bf16 v[144:147], v[250:253], v[214:217], v[144:147]
	ds_read_b128 v[250:253], v201 offset:4480
	s_waitcnt lgkmcnt(3)
	v_mfma_f32_16x16x32_bf16 v[156:159], v[218:221], v[210:213], v[156:159]
	v_mfma_f32_16x16x32_bf16 v[152:155], v[218:221], v[214:217], v[152:155]
	ds_read_b128 v[218:221], v201 offset:8832
	s_waitcnt lgkmcnt(3)
	v_mfma_f32_16x16x32_bf16 v[92:95], v[238:241], v[210:213], v[92:95]
	v_mfma_f32_16x16x32_bf16 v[100:103], v[238:241], v[214:217], v[100:103]
	ds_read_b128 v[210:213], v205 offset:128
	ds_read_b128 v[214:217], v205 offset:4480
	ds_read_b128 v[238:241], v201 offset:13184
	s_waitcnt lgkmcnt(2)
	v_mfma_f32_16x16x32_bf16 v[108:111], v[246:249], v[210:213], v[108:111]
	s_waitcnt lgkmcnt(1)
	v_mfma_f32_16x16x32_bf16 v[104:107], v[246:249], v[214:217], v[104:107]
	ds_read_b128 v[246:249], v201 offset:17536
	v_mfma_f32_16x16x32_bf16 v[116:119], v[250:253], v[210:213], v[116:119]
	v_mfma_f32_16x16x32_bf16 v[112:115], v[250:253], v[214:217], v[112:115]
	ds_read_b128 v[250:253], v201 offset:21888
	v_mfma_f32_16x16x32_bf16 v[124:127], v[218:221], v[210:213], v[124:127]
	v_mfma_f32_16x16x32_bf16 v[120:123], v[218:221], v[214:217], v[120:123]
	ds_read_b128 v[242:245], v201 offset:26240
	s_waitcnt lgkmcnt(3)
	v_mfma_f32_16x16x32_bf16 v[222:225], v[238:241], v[210:213], v[132:135]
	s_nop 2
	v_mfma_f32_16x16x32_bf16 v[128:131], v[238:241], v[214:217], v[128:131]
	s_waitcnt lgkmcnt(2)
	v_mfma_f32_16x16x32_bf16 v[218:221], v[246:249], v[210:213], v[140:143]
	v_mfma_f32_16x16x32_bf16 v[226:229], v[246:249], v[214:217], v[136:139]
	ds_read_b128 v[246:249], v201 offset:30592
	s_waitcnt lgkmcnt(2)
; #define LAS __attribute__((address_space(3)))
; __device__ __forceinline__ void attn_unit(const bf16* proj, unsigned char* ws, LAS unsigned char* lds, int a) {
;     ...
; #pragma unroll
;         for (int s = 0; s < 4; ++s) {
;             const bf16x8 qa = *(const LAS bf16x8*)(qbase + 64 * s), qb = *(const LAS bf16x8*)(qbase + 16 * QK_STRIDE + 64 * s);
; #pragma unroll
;             for (int kt = 0; kt < 8; ++kt) {
;                 const bf16x8 kf = *(const LAS bf16x8*)(KS + (16 * kt + fr) * QK_STRIDE + (32 * s + 8 * fq) * 2);
;                 st[0][kt] = __builtin_amdgcn_mfma_f32_16x16x32_bf16(kf, qa, st[0][kt], 0, 0, 0);
;                 st[1][kt] = __builtin_amdgcn_mfma_f32_16x16x32_bf16(kf, qb, st[1][kt], 0, 0, 0);
;             }
;         }
;         bf16x8 pb[2][4];
; #pragma unroll
;         for (int rt = 0; rt < 2; ++rt) {
;             const int qi = rq * 32 + rt * 16 + fr;
;             if (kb != n) {
;                 const int sgn = (kb < n) ? 1 : -1, dbase = sgn * (4 * fq - qi);
; #pragma unroll
;                 for (int kt = 0; kt < 8; ++kt)
; #pragma unroll
;                     for (int r = 0; r < 4; ++r) { const int dd = dbase + sgn * (16 * kt + r); st[rt][kt][r] += __builtin_bit_cast(float, (unsigned)(dd >> 31) & 0xF149F2CAu); }
;             }
	v_mfma_f32_16x16x32_bf16 v[148:151], v[250:253], v[210:213], v[148:151]
	v_mfma_f32_16x16x32_bf16 v[230:233], v[250:253], v[214:217], v[144:147]
	s_waitcnt lgkmcnt(1)
	v_mfma_f32_16x16x32_bf16 v[156:159], v[242:245], v[210:213], v[156:159]
	v_mfma_f32_16x16x32_bf16 v[234:237], v[242:245], v[214:217], v[152:155]
	s_waitcnt lgkmcnt(0)
	v_mfma_f32_16x16x32_bf16 v[214:217], v[246:249], v[214:217], v[100:103]
	ds_read_b128 v[238:241], v205 offset:192
	ds_read_b128 v[242:245], v205 offset:4544
	s_nop 0
	ds_read_b128 v[100:103], v201 offset:192
	s_waitcnt lgkmcnt(0)
	v_mfma_f32_16x16x32_bf16 v[140:143], v[100:103], v[242:245], v[104:107]
	s_nop 2
	ds_read_b128 v[104:107], v201 offset:4544
	v_mfma_f32_16x16x32_bf16 v[210:213], v[246:249], v[210:213], v[92:95]
	v_mfma_f32_16x16x32_bf16 v[92:95], v[100:103], v[238:241], v[108:111]
	s_nop 2
	ds_read_b128 v[108:111], v201 offset:8896
	s_waitcnt lgkmcnt(1)
	v_mfma_f32_16x16x32_bf16 v[136:139], v[104:107], v[242:245], v[112:115]
	s_nop 2
	ds_read_b128 v[112:115], v201 offset:13248
	v_mfma_f32_16x16x32_bf16 v[100:103], v[104:107], v[238:241], v[116:119]
	s_waitcnt lgkmcnt(1)
	v_mfma_f32_16x16x32_bf16 v[104:107], v[108:111], v[238:241], v[124:127]
	v_mfma_f32_16x16x32_bf16 v[132:135], v[108:111], v[242:245], v[120:123]
	s_waitcnt lgkmcnt(0)
	v_mfma_f32_16x16x32_bf16 v[108:111], v[112:115], v[238:241], v[222:225]
	v_mfma_f32_16x16x32_bf16 v[128:131], v[112:115], v[242:245], v[128:131]
	ds_read_b128 v[112:115], v201 offset:17600
	s_waitcnt lgkmcnt(0)
	v_mfma_f32_16x16x32_bf16 v[144:147], v[112:115], v[238:241], v[218:221]
	v_mfma_f32_16x16x32_bf16 v[124:127], v[112:115], v[242:245], v[226:229]
	ds_read_b128 v[112:115], v201 offset:21952
	s_waitcnt lgkmcnt(0)
	v_mfma_f32_16x16x32_bf16 v[148:151], v[112:115], v[238:241], v[148:151]
	v_mfma_f32_16x16x32_bf16 v[120:123], v[112:115], v[242:245], v[230:233]
	ds_read_b128 v[112:115], v201 offset:26304
	s_waitcnt lgkmcnt(0)
	v_mfma_f32_16x16x32_bf16 v[152:155], v[112:115], v[238:241], v[156:159]
	v_mfma_f32_16x16x32_bf16 v[116:119], v[112:115], v[242:245], v[234:237]
	ds_read_b128 v[112:115], v201 offset:30656
	s_waitcnt lgkmcnt(0)
	v_mfma_f32_16x16x32_bf16 v[156:159], v[112:115], v[238:241], v[210:213]
	s_nop 2
	v_mfma_f32_16x16x32_bf16 v[112:115], v[112:115], v[242:245], v[214:217]
	s_nop 3
	s_cbranch_scc1 .LBB0_610
	s_cmp_lt_u32 s70, s69
	s_cbranch_scc0 .Lam_a_next
	v_cmp_gt_i32_e32 vcc, 0, v181
	v_cndmask_b32_e32 v92, v92, v171, vcc
	v_cmp_gt_i32_e32 vcc, -1, v181
	v_cndmask_b32_e32 v93, v93, v171, vcc
	v_cmp_gt_i32_e32 vcc, -2, v181
	v_cndmask_b32_e32 v94, v94, v171, vcc
	v_cmp_gt_i32_e32 vcc, -3, v181
	v_cndmask_b32_e32 v95, v95, v171, vcc
	v_cmp_gt_i32_e32 vcc, -16, v181
	v_cndmask_b32_e32 v100, v100, v171, vcc
	v_cmp_gt_i32_e32 vcc, 0xffffffef, v181
	v_cndmask_b32_e32 v101, v101, v171, vcc
	v_cmp_gt_i32_e32 vcc, 0xffffffee, v181
	v_cndmask_b32_e32 v102, v102, v171, vcc
	v_cmp_gt_i32_e32 vcc, 0xffffffed, v181
	v_cndmask_b32_e32 v103, v103, v171, vcc
	v_cmp_gt_i32_e32 vcc, 0xffffffe0, v181
	v_cndmask_b32_e32 v104, v104, v171, vcc
	v_cmp_gt_i32_e32 vcc, 0xffffffdf, v181
	v_cndmask_b32_e32 v105, v105, v171, vcc
	v_cmp_gt_i32_e32 vcc, 0xffffffde, v181
	v_cndmask_b32_e32 v106, v106, v171, vcc
	v_cmp_gt_i32_e32 vcc, 0xffffffdd, v181
	v_cndmask_b32_e32 v107, v107, v171, vcc
	v_cmp_gt_i32_e32 vcc, 0xffffffd0, v181
	v_cndmask_b32_e32 v108, v108, v171, vcc
	v_cmp_gt_i32_e32 vcc, 0xffffffcf, v181
	v_cndmask_b32_e32 v109, v109, v171, vcc
	v_cmp_gt_i32_e32 vcc, 0xffffffce, v181
	v_cndmask_b32_e32 v110, v110, v171, vcc
	v_cmp_gt_i32_e32 vcc, 0xffffffcd, v181
	v_cndmask_b32_e32 v111, v111, v171, vcc
	v_cmp_gt_i32_e32 vcc, 0xffffffc0, v181
	v_cndmask_b32_e32 v144, v144, v171, vcc
	v_cmp_gt_i32_e32 vcc, 0xffffffbf, v181
	v_cndmask_b32_e32 v145, v145, v171, vcc
	v_cmp_gt_i32_e32 vcc, 0xffffffbe, v181
	v_cndmask_b32_e32 v146, v146, v171, vcc
	v_cmp_gt_i32_e32 vcc, 0xffffffbd, v181
	v_cndmask_b32_e32 v147, v147, v171, vcc
	v_cmp_gt_i32_e32 vcc, 0xffffffb0, v181
	v_cndmask_b32_e32 v148, v148, v171, vcc
	v_cmp_gt_i32_e32 vcc, 0xffffffaf, v181
	v_cndmask_b32_e32 v149, v149, v171, vcc
	v_cmp_gt_i32_e32 vcc, 0xffffffae, v181
	v_cndmask_b32_e32 v150, v150, v171, vcc
	v_cmp_gt_i32_e32 vcc, 0xffffffad, v181
	v_cndmask_b32_e32 v151, v151, v171, vcc
	v_cmp_gt_i32_e32 vcc, 0xffffffa0, v181
	v_cndmask_b32_e32 v152, v152, v171, vcc
	v_cmp_gt_i32_e32 vcc, 0xffffff9f, v181
	v_cndmask_b32_e32 v153, v153, v171, vcc
	v_cmp_gt_i32_e32 vcc, 0xffffff9e, v181
	v_cndmask_b32_e32 v154, v154, v171, vcc
	v_cmp_gt_i32_e32 vcc, 0xffffff9d, v181
	v_cndmask_b32_e32 v155, v155, v171, vcc
	v_cmp_gt_i32_e32 vcc, 0xffffff90, v181
	v_cndmask_b32_e32 v156, v156, v171, vcc
	v_cmp_gt_i32_e32 vcc, 0xffffff8f, v181
	v_cndmask_b32_e32 v157, v157, v171, vcc
	v_cmp_gt_i32_e32 vcc, 0xffffff8e, v181
	v_cndmask_b32_e32 v158, v158, v171, vcc
	v_cmp_gt_i32_e32 vcc, 0xffffff8d, v181
	v_cndmask_b32_e32 v159, v159, v171, vcc
	s_branch .LBB0_610
